# combination: task table in LDS plus the two redundant task-loop barriers removed, on top of the batched epilogues
# speedup vs baseline: 1.0068x; 1.0057x over previous
.LBB0_223:
	s_or_b64 exec, exec, s[4:5]
	s_add_i32 s0, 0, 0x24000
	s_mov_b64 s[4:5], src_shared_base
	s_cmp_lg_u32 s0, -1
	s_cselect_b32 s0, s0, 0
	s_cselect_b32 s4, s5, 0
	v_mov_b32_e32 v4, s0
	v_mov_b32_e32 v5, s4
	s_waitcnt lgkmcnt(0)
	s_barrier
	ds_read_b32 v4, v4
	s_movk_i32 s0, 0x548
	s_mov_b64 s[4:5], -1
	s_waitcnt lgkmcnt(0)
	v_cmp_gt_i32_e32 vcc, s0, v4
	s_mov_b64 s[6:7], exec
	v_writelane_b32 v254, s6, 48
	s_nop 1
	v_writelane_b32 v254, s7, 49
	s_and_b64 s[6:7], s[6:7], vcc
	s_mov_b64 exec, s[6:7]
	s_cbranch_execz .LBB0_218
	v_lshlrev_b32_e32 v5, 2, v4
	v_add_u32_e32 v5, 0x24100, v5
	ds_read_b32 v10, v5
	s_mov_b32 s0, 0x10000
	s_waitcnt lgkmcnt(0)
	v_cmp_gt_u32_e64 s[4:5], s0, v10
	s_nop 1
	v_writelane_b32 v254, s4, 50
	s_mov_b32 s0, 0xffff
	v_cmp_lt_u32_e64 s[6:7], s0, v10
	v_writelane_b32 v254, s5, 51
	v_cmp_ne_u32_sdwa s[4:5], v10, v206 src0_sel:WORD_1 src1_sel:DWORD
	v_writelane_b32 v254, s6, 52
	v_and_b32_e32 v12, 0xffff, v10
	s_and_b64 s[4:5], s[6:7], s[4:5]
	v_writelane_b32 v254, s7, 53
	s_and_saveexec_b64 s[6:7], s[4:5]
	s_xor_b64 s[6:7], exec, s[6:7]
	v_writelane_b32 v254, s6, 54
	s_nop 1
	v_writelane_b32 v254, s7, 55
	s_cbranch_execz .LBB0_314
	v_cmp_gt_i16_sdwa s[6:7], v10, v206 src0_sel:WORD_1 src1_sel:DWORD
	s_mov_b64 s[8:9], 0
	s_mov_b64 s[4:5], 0
	s_and_saveexec_b64 s[10:11], s[6:7]
	s_xor_b64 s[6:7], exec, s[10:11]
	s_cbranch_execz .LBB0_228
	v_mov_b32_e32 v0, 3
	v_cmp_ne_u16_sdwa s[4:5], v10, v0 src0_sel:WORD_1 src1_sel:DWORD
	s_and_b64 s[8:9], s[4:5], exec
	s_mov_b64 s[4:5], exec
	s_andn2_saveexec_b64 s[6:7], s[6:7]
	s_cbranch_execnz .LBB0_229
